# norm rows loop: xor 8/4/2/1 steps of the wave sum via v_mov_b32_dpp instead of ds_bpermute round trips (bit-identical sums)
# speedup vs baseline: 1.0124x; 1.0124x over previous
.LBB0_180:
	v_readlane_b32 s0, v253, 39
	s_movk_i32 s3, 0x4000
	v_add_u32_e32 v0, 0xffffc000, v50
	v_mov_b32_e32 v34, s0
	v_readlane_b32 s0, v253, 37
	v_cmp_gt_i32_e32 vcc, s3, v50
	v_min_i32_e32 v12, 0x4000, v50
	v_mov_b32_e32 v35, s0
	v_readlane_b32 s0, v253, 40
	v_cndmask_b32_e32 v3, 0, v51, vcc
	v_cndmask_b32_e32 v2, v0, v50, vcc
	v_mov_b32_e32 v36, s0
	v_readlane_b32 s0, v253, 38
	v_cndmask_b32_e32 v5, v34, v35, vcc
	v_lshlrev_b64 v[2:3], 12, v[2:3]
	v_mov_b32_e32 v37, s0
	v_cndmask_b32_e32 v4, v36, v37, vcc
	v_lshl_add_u64 v[2:3], v[4:5], 0, v[2:3]
	v_lshlrev_b32_e32 v0, 2, v52
	v_lshl_add_u64 v[2:3], v[2:3], 0, v[0:1]
	global_load_dwordx4 v[30:33], v[2:3], off
	global_load_dwordx4 v[26:29], v[2:3], off offset:1024
	s_waitcnt lgkmcnt(0)
	global_load_dwordx4 v[18:21], v[2:3], off offset:2048
	s_nop 0
	global_load_dwordx4 v[2:5], v[2:3], off offset:3072
	s_nop 0
	global_load_dwordx4 v[80:83], v[54:55], off
	v_lshl_add_u64 v[10:11], s[42:43], 0, v[50:51]
	v_ashrrev_i32_e32 v12, 11, v12
	v_readlane_b32 s0, v253, 41
	v_mov_b64_e32 v[6:7], s[36:37]
	v_lshl_add_u64 v[70:71], s[42:43], 0, v[10:11]
	v_add_u32_e32 v11, s0, v12
	s_movk_i32 s0, 0x3000
	v_mad_i64_i32 v[6:7], s[0:1], v11, s0, v[6:7]
	s_mov_b64 s[0:1], 0x1000
	s_nop 0
	v_lshl_add_u64 v[92:93], v[6:7], 0, s[0:1]
	v_lshl_add_u64 v[12:13], v[92:93], 0, v[0:1]
	global_load_dwordx4 v[84:87], v[12:13], off
	v_lshl_add_u64 v[94:95], v[6:7], 0, v[0:1]
	global_load_dwordx4 v[88:91], v[94:95], off
	v_lshl_add_u64 v[8:9], v[62:63], 0, v[58:59]
	s_mov_b32 s0, 0x133c000
	v_add_co_u32_e32 v72, vcc, s0, v8
	s_movk_i32 s2, 0x4800
	s_nop 0
	v_addc_co_u32_e32 v73, vcc, 0, v9, vcc
	v_cmp_gt_i32_e64 s[0:1], s2, v10
	v_cmp_gt_i32_e32 vcc, s2, v70
	v_mov_b32_e32 v65, v1
	v_cndmask_b32_e64 v38, v50, v10, s[0:1]
	v_ashrrev_i32_e32 v39, 31, v38
	v_add_u32_e32 v40, 0xffffc000, v38
	v_cmp_gt_i32_e64 s[4:5], s3, v38
	s_waitcnt vmcnt(6)
	v_mov_b32_e32 v8, v31
	s_waitcnt vmcnt(5)
	v_mov_b32_e32 v9, v27
	v_mov_b32_e32 v6, v30
	v_mov_b32_e32 v7, v26
	s_waitcnt vmcnt(4)
	v_mov_b32_e32 v14, v19
	s_waitcnt vmcnt(3)
	v_mov_b32_e32 v15, v3
	v_pk_mul_f32 v[8:9], v[8:9], v[8:9]
	v_mov_b32_e32 v10, v32
	v_mov_b32_e32 v11, v28
	v_mov_b32_e32 v12, v18
	v_mov_b32_e32 v13, v2
	v_pk_mul_f32 v[14:15], v[14:15], v[14:15]
	v_pk_fma_f32 v[6:7], v[6:7], v[6:7], v[8:9]
	v_mov_b32_e32 v16, v33
	v_mov_b32_e32 v17, v29
	v_mov_b32_e32 v22, v20
	v_mov_b32_e32 v23, v4
	v_pk_fma_f32 v[8:9], v[12:13], v[12:13], v[14:15]
	v_pk_fma_f32 v[6:7], v[10:11], v[10:11], v[6:7]
	v_mov_b32_e32 v24, v21
	v_mov_b32_e32 v25, v5
	v_pk_fma_f32 v[8:9], v[22:23], v[22:23], v[8:9]
	v_pk_fma_f32 v[6:7], v[16:17], v[16:17], v[6:7]
	v_pk_fma_f32 v[8:9], v[24:25], v[24:25], v[8:9]
	v_add_f32_e32 v6, v6, v7
	v_add_f32_e32 v6, v6, v8
	v_add_f32_e32 v8, v6, v9
	ds_bpermute_b32 v9, v53, v8
	v_cndmask_b32_e32 v10, v50, v70, vcc
	v_cndmask_b32_e64 v7, 0, v39, s[4:5]
	v_cndmask_b32_e64 v6, v40, v38, s[4:5]
	v_add_u32_e32 v14, 0xffffc000, v10
	s_waitcnt lgkmcnt(0)
	v_add_f32_e32 v11, v8, v9
	ds_bpermute_b32 v12, v74, v11
	v_cndmask_b32_e64 v9, v34, v35, s[4:5]
	v_cndmask_b32_e64 v8, v36, v37, s[4:5]
	v_cmp_gt_i32_e64 s[4:5], s3, v10
	v_ashrrev_i32_e32 v13, 31, v10
	s_waitcnt lgkmcnt(0)
	v_add_f32_e32 v15, v11, v12
	s_nop 1
	v_mov_b32_dpp v16, v15 row_ror:8 row_mask:0xf bank_mask:0xf
	v_cndmask_b32_e64 v10, v14, v10, s[4:5]
	v_cndmask_b32_e64 v11, 0, v13, s[4:5]
	v_lshlrev_b64 v[6:7], 12, v[6:7]
	v_lshl_add_u64 v[6:7], v[8:9], 0, v[6:7]
	s_waitcnt lgkmcnt(0)
	v_add_f32_e32 v14, v15, v16
	s_nop 1
	v_mov_b32_dpp v15, v14 row_ror:4 row_mask:0xf bank_mask:0xf
	v_lshlrev_b64 v[8:9], 12, v[10:11]
	v_cndmask_b32_e64 v13, v34, v35, s[4:5]
	v_cndmask_b32_e64 v12, v36, v37, s[4:5]
	v_lshl_add_u64 v[8:9], v[12:13], 0, v[8:9]
	s_waitcnt lgkmcnt(0)
	v_add_f32_e32 v10, v14, v15
	s_nop 1
	v_mov_b32_dpp v11, v10 quad_perm:[2,3,0,1] row_mask:0xf bank_mask:0xf
	v_lshl_add_u64 v[6:7], v[6:7], 0, v[0:1]
	v_lshl_add_u64 v[8:9], v[8:9], 0, v[0:1]
	global_load_dwordx4 v[46:49], v[6:7], off
	global_load_dwordx4 v[42:45], v[6:7], off offset:1024
	global_load_dwordx4 v[38:41], v[6:7], off offset:2048
	global_load_dwordx4 v[34:37], v[6:7], off offset:3072
	global_load_dwordx4 v[22:25], v[8:9], off
	global_load_dwordx4 v[14:17], v[8:9], off offset:1024
	s_waitcnt lgkmcnt(0)
	v_add_f32_e32 v10, v10, v11
	s_nop 1
	v_mov_b32_dpp v11, v10 quad_perm:[1,0,3,2] row_mask:0xf bank_mask:0xf
	s_waitcnt vmcnt(7)
	v_pk_add_f32 v[84:85], v[84:85], 1.0 op_sel_hi:[1,0]
	v_pk_add_f32 v[86:87], v[86:87], 1.0 op_sel_hi:[1,0]
	s_waitcnt lgkmcnt(0)
	v_add_f32_e32 v6, v10, v11
	v_fmamk_f32 v6, v6, 0x3a800000, v196
	v_mul_f32_e32 v7, 0x4b800000, v6
	v_cmp_gt_f32_e64 s[4:5], s33, v6
	s_waitcnt vmcnt(1)
	v_mul_f32_e32 v71, v23, v23
	v_cndmask_b32_e64 v6, v6, v7, s[4:5]
	v_rsq_f32_e32 v67, v6
	global_load_dwordx4 v[10:13], v[8:9], off offset:2048
	s_nop 0
	global_load_dwordx4 v[6:9], v[8:9], off offset:3072
	s_waitcnt vmcnt(2)
	v_mul_f32_e32 v79, v15, v15
	v_fmac_f32_e32 v71, v22, v22
	v_mul_f32_e32 v69, 0x45800000, v67
	v_cndmask_b32_e64 v96, v67, v69, s[4:5]
	v_pk_mul_f32 v[30:31], v[30:31], v[96:97] op_sel_hi:[1,0]
	v_pk_mul_f32 v[32:33], v[32:33], v[96:97] op_sel_hi:[1,0]
	v_pk_mul_f32 v[30:31], v[30:31], v[80:81]
	v_pk_mul_f32 v[32:33], v[32:33], v[82:83]
	v_pk_fma_f32 v[30:31], v[30:31], v[84:85], v[88:89]
	v_pk_fma_f32 v[32:33], v[32:33], v[86:87], v[90:91]
	v_cvt_pk_bf16_f32 v30, v30, v31
	v_cvt_pk_bf16_f32 v31, v32, v33
	global_store_dwordx2 v[72:73], v[30:31], off
	global_load_dwordx4 v[30:33], v[54:55], off offset:1024
	v_lshl_add_u64 v[80:81], v[92:93], 0, v[64:65]
	global_load_dwordx4 v[80:83], v[80:81], off
	s_nop 0
	global_load_dwordx4 v[84:87], v[94:95], off offset:1024
	v_pk_mul_f32 v[26:27], v[26:27], v[96:97] op_sel_hi:[1,0]
	v_pk_mul_f32 v[28:29], v[28:29], v[96:97] op_sel_hi:[1,0]
	v_mov_b32_e32 v67, v1
	v_pk_mul_f32 v[18:19], v[18:19], v[96:97] op_sel_hi:[1,0]
	v_pk_mul_f32 v[20:21], v[20:21], v[96:97] op_sel_hi:[1,0]
	v_mov_b32_e32 v69, v1
	v_fmac_f32_e32 v79, v14, v14
	v_fmac_f32_e32 v71, v24, v24
	v_fmac_f32_e32 v79, v16, v16
	v_fmac_f32_e32 v71, v25, v25
	v_fmac_f32_e32 v79, v17, v17
	v_pk_mul_f32 v[2:3], v[2:3], v[96:97] op_sel_hi:[1,0]
	v_pk_mul_f32 v[4:5], v[4:5], v[96:97] op_sel_hi:[1,0]
	s_waitcnt vmcnt(2)
	v_pk_mul_f32 v[26:27], v[26:27], v[30:31]
	v_pk_mul_f32 v[28:29], v[28:29], v[32:33]
	s_waitcnt vmcnt(1)
	v_pk_add_f32 v[30:31], v[80:81], 1.0 op_sel_hi:[1,0]
	v_pk_add_f32 v[32:33], v[82:83], 1.0 op_sel_hi:[1,0]
	s_waitcnt vmcnt(0)
	v_pk_fma_f32 v[26:27], v[26:27], v[30:31], v[84:85]
	v_pk_fma_f32 v[28:29], v[28:29], v[32:33], v[86:87]
	v_cvt_pk_bf16_f32 v26, v26, v27
	v_cvt_pk_bf16_f32 v27, v28, v29
	global_store_dwordx2 v[72:73], v[26:27], off offset:512
	global_load_dwordx4 v[26:29], v[54:55], off offset:2048
	v_lshl_add_u64 v[30:31], v[92:93], 0, v[66:67]
	global_load_dwordx4 v[30:33], v[30:31], off
	s_nop 0
	global_load_dwordx4 v[80:83], v[94:95], off offset:2048
	v_lshl_add_u64 v[84:85], v[92:93], 0, v[68:69]
	s_waitcnt vmcnt(2)
	v_pk_mul_f32 v[18:19], v[18:19], v[26:27]
	v_pk_mul_f32 v[20:21], v[20:21], v[28:29]
	s_waitcnt vmcnt(1)
	v_pk_add_f32 v[26:27], v[30:31], 1.0 op_sel_hi:[1,0]
	v_pk_add_f32 v[28:29], v[32:33], 1.0 op_sel_hi:[1,0]
	s_waitcnt vmcnt(0)
	v_pk_fma_f32 v[18:19], v[18:19], v[26:27], v[80:81]
	v_pk_fma_f32 v[20:21], v[20:21], v[28:29], v[82:83]
	v_cvt_pk_bf16_f32 v18, v18, v19
	v_cvt_pk_bf16_f32 v19, v20, v21
	global_store_dwordx2 v[72:73], v[18:19], off offset:1024
	global_load_dwordx4 v[26:29], v[54:55], off offset:3072
	global_load_dwordx4 v[30:33], v[84:85], off
	global_load_dwordx4 v[80:83], v[94:95], off offset:3072
	v_mul_f32_e32 v18, v47, v47
	v_mul_f32_e32 v19, v43, v43
	v_mul_f32_e32 v20, v39, v39
	v_fmac_f32_e32 v18, v46, v46
	v_fmac_f32_e32 v19, v42, v42
	v_mul_f32_e32 v84, v11, v11
	v_mul_f32_e32 v21, v35, v35
	v_fmac_f32_e32 v20, v38, v38
	v_mul_f32_e32 v85, v7, v7
	v_fmac_f32_e32 v18, v48, v48
	v_fmac_f32_e32 v19, v44, v44
	v_fmac_f32_e32 v84, v10, v10
	v_fmac_f32_e32 v21, v34, v34
	v_fmac_f32_e32 v20, v40, v40
	v_fmac_f32_e32 v85, v6, v6
	v_fmac_f32_e32 v18, v49, v49
	v_fmac_f32_e32 v19, v45, v45
	v_fmac_f32_e32 v84, v12, v12
	v_fmac_f32_e32 v21, v36, v36
	v_fmac_f32_e32 v20, v41, v41
	v_fmac_f32_e32 v85, v8, v8
	v_add_f32_e32 v18, v18, v19
	v_fmac_f32_e32 v84, v13, v13
	v_add_f32_e32 v19, v71, v79
	v_fmac_f32_e32 v21, v37, v37
	v_fmac_f32_e32 v85, v9, v9
	v_add_f32_e32 v18, v18, v20
	v_add_f32_e32 v19, v19, v84
	v_add_f32_e32 v18, v18, v21
	v_add_f32_e32 v19, v19, v85
	ds_bpermute_b32 v20, v53, v18
	ds_bpermute_b32 v21, v53, v19
	s_waitcnt lgkmcnt(1)
	v_add_f32_e32 v18, v18, v20
	s_waitcnt lgkmcnt(0)
	v_add_f32_e32 v19, v19, v21
	ds_bpermute_b32 v20, v74, v18
	ds_bpermute_b32 v21, v74, v19
	s_waitcnt lgkmcnt(1)
	v_add_f32_e32 v18, v18, v20
	s_waitcnt lgkmcnt(0)
	v_add_f32_e32 v19, v19, v21
	v_mov_b32_dpp v20, v18 row_ror:8 row_mask:0xf bank_mask:0xf
	s_nop 0
	v_mov_b32_dpp v21, v19 row_ror:8 row_mask:0xf bank_mask:0xf
	s_waitcnt lgkmcnt(1)
	v_add_f32_e32 v18, v18, v20
	s_waitcnt lgkmcnt(0)
	v_add_f32_e32 v19, v19, v21
	v_mov_b32_dpp v20, v18 row_ror:4 row_mask:0xf bank_mask:0xf
	s_nop 0
	v_mov_b32_dpp v21, v19 row_ror:4 row_mask:0xf bank_mask:0xf
	s_waitcnt lgkmcnt(1)
	v_add_f32_e32 v18, v18, v20
	s_waitcnt lgkmcnt(0)
	v_add_f32_e32 v19, v19, v21
	v_mov_b32_dpp v20, v18 quad_perm:[2,3,0,1] row_mask:0xf bank_mask:0xf
	s_nop 0
	v_mov_b32_dpp v21, v19 quad_perm:[2,3,0,1] row_mask:0xf bank_mask:0xf
	s_waitcnt lgkmcnt(1)
	v_add_f32_e32 v20, v18, v20
	s_waitcnt lgkmcnt(0)
	v_add_f32_e32 v18, v19, v21
	v_mov_b32_dpp v21, v20 quad_perm:[1,0,3,2] row_mask:0xf bank_mask:0xf
	s_nop 0
	v_mov_b32_dpp v19, v18 quad_perm:[1,0,3,2] row_mask:0xf bank_mask:0xf
	s_waitcnt vmcnt(2)
	v_pk_mul_f32 v[2:3], v[2:3], v[26:27]
	v_pk_mul_f32 v[4:5], v[4:5], v[28:29]
	s_waitcnt vmcnt(1)
	v_pk_add_f32 v[26:27], v[30:31], 1.0 op_sel_hi:[1,0]
	v_pk_add_f32 v[28:29], v[32:33], 1.0 op_sel_hi:[1,0]
	s_waitcnt vmcnt(0)
	v_pk_fma_f32 v[2:3], v[2:3], v[26:27], v[80:81]
	v_pk_fma_f32 v[4:5], v[4:5], v[28:29], v[82:83]
	v_cvt_pk_bf16_f32 v2, v2, v3
	v_cvt_pk_bf16_f32 v3, v4, v5
	global_store_dwordx2 v[72:73], v[2:3], off offset:1536
	s_and_saveexec_b64 s[12:13], s[0:1]
	s_cbranch_execz .LBB0_182
	v_add_u32_e32 v2, s42, v50
	v_min_i32_e32 v2, 0x4000, v2
	v_ashrrev_i32_e32 v2, 11, v2
	v_readlane_b32 s0, v253, 41
	s_waitcnt lgkmcnt(1)
	v_add_f32_e32 v71, v20, v21
	v_fmamk_f32 v71, v71, 0x3a800000, v196
	v_add_u32_e32 v4, s0, v2
	v_mov_b64_e32 v[2:3], s[36:37]
	s_movk_i32 s0, 0x3000
	v_mad_i64_i32 v[30:31], s[0:1], v4, s0, v[2:3]
	s_mov_b64 s[0:1], 0x1000
	s_nop 0
	v_lshl_add_u64 v[72:73], v[30:31], 0, s[0:1]
	v_lshl_add_u64 v[26:27], v[72:73], 0, v[0:1]
	global_load_dwordx4 v[2:5], v[54:55], off
	v_lshl_add_u64 v[80:81], v[30:31], 0, v[0:1]
	global_load_dwordx4 v[26:29], v[26:27], off
	v_mul_f32_e32 v79, 0x4b800000, v71
	global_load_dwordx4 v[30:33], v[80:81], off
	v_cmp_gt_f32_e64 s[0:1], s33, v71
	v_lshl_add_u64 v[82:83], v[72:73], 0, v[64:65]
	v_lshl_add_u64 v[20:21], v[60:61], 0, v[58:59]
	v_cndmask_b32_e64 v71, v71, v79, s[0:1]
	v_rsq_f32_e32 v71, v71
	s_mov_b32 s2, 0x133c000
	v_add_co_u32_e64 v20, s[4:5], s2, v20
	v_mul_f32_e32 v65, 0x45800000, v71
	v_cndmask_b32_e64 v84, v71, v65, s[0:1]
	v_pk_mul_f32 v[46:47], v[46:47], v[84:85] op_sel_hi:[1,0]
	v_pk_mul_f32 v[48:49], v[48:49], v[84:85] op_sel_hi:[1,0]
	v_addc_co_u32_e64 v21, s[4:5], 0, v21, s[4:5]
	v_pk_mul_f32 v[42:43], v[42:43], v[84:85] op_sel_hi:[1,0]
	v_pk_mul_f32 v[44:45], v[44:45], v[84:85] op_sel_hi:[1,0]
	v_pk_mul_f32 v[38:39], v[38:39], v[84:85] op_sel_hi:[1,0]
	v_pk_mul_f32 v[40:41], v[40:41], v[84:85] op_sel_hi:[1,0]
	v_pk_mul_f32 v[34:35], v[34:35], v[84:85] op_sel_hi:[1,0]
	v_pk_mul_f32 v[36:37], v[36:37], v[84:85] op_sel_hi:[1,0]
	s_waitcnt vmcnt(2)
	v_pk_mul_f32 v[2:3], v[46:47], v[2:3]
	v_pk_mul_f32 v[4:5], v[48:49], v[4:5]
	s_waitcnt vmcnt(1)
	v_pk_add_f32 v[26:27], v[26:27], 1.0 op_sel_hi:[1,0]
	v_pk_add_f32 v[28:29], v[28:29], 1.0 op_sel_hi:[1,0]
	s_waitcnt vmcnt(0)
	v_pk_fma_f32 v[2:3], v[2:3], v[26:27], v[30:31]
	v_pk_fma_f32 v[4:5], v[4:5], v[28:29], v[32:33]
	v_cvt_pk_bf16_f32 v2, v2, v3
	v_cvt_pk_bf16_f32 v3, v4, v5
	global_store_dwordx2 v[20:21], v[2:3], off
	global_load_dwordx4 v[2:5], v[54:55], off offset:1024
	s_nop 0
	global_load_dwordx4 v[26:29], v[82:83], off
	global_load_dwordx4 v[30:33], v[80:81], off offset:1024
	v_lshl_add_u64 v[46:47], v[72:73], 0, v[66:67]
	s_waitcnt vmcnt(2)
	v_pk_mul_f32 v[2:3], v[42:43], v[2:3]
	s_waitcnt vmcnt(1)
	v_pk_add_f32 v[26:27], v[26:27], 1.0 op_sel_hi:[1,0]
	v_pk_mul_f32 v[4:5], v[44:45], v[4:5]
	v_pk_add_f32 v[28:29], v[28:29], 1.0 op_sel_hi:[1,0]
	s_waitcnt vmcnt(0)
	v_pk_fma_f32 v[2:3], v[2:3], v[26:27], v[30:31]
	v_pk_fma_f32 v[4:5], v[4:5], v[28:29], v[32:33]
	v_cvt_pk_bf16_f32 v2, v2, v3
	v_cvt_pk_bf16_f32 v3, v4, v5
	global_store_dwordx2 v[20:21], v[2:3], off offset:512
	global_load_dwordx4 v[2:5], v[54:55], off offset:2048
	s_nop 0
	global_load_dwordx4 v[26:29], v[46:47], off
	global_load_dwordx4 v[30:33], v[80:81], off offset:2048
	v_lshl_add_u64 v[42:43], v[72:73], 0, v[68:69]
	s_waitcnt vmcnt(2)
	v_pk_mul_f32 v[2:3], v[38:39], v[2:3]
	s_waitcnt vmcnt(1)
	v_pk_add_f32 v[26:27], v[26:27], 1.0 op_sel_hi:[1,0]
	v_pk_mul_f32 v[4:5], v[40:41], v[4:5]
	v_pk_add_f32 v[28:29], v[28:29], 1.0 op_sel_hi:[1,0]
	s_waitcnt vmcnt(0)
	v_pk_fma_f32 v[2:3], v[2:3], v[26:27], v[30:31]
	v_pk_fma_f32 v[4:5], v[4:5], v[28:29], v[32:33]
	v_cvt_pk_bf16_f32 v2, v2, v3
	v_cvt_pk_bf16_f32 v3, v4, v5
	global_store_dwordx2 v[20:21], v[2:3], off offset:1024
	global_load_dwordx4 v[2:5], v[54:55], off offset:3072
	s_nop 0
	global_load_dwordx4 v[26:29], v[42:43], off
	global_load_dwordx4 v[30:33], v[80:81], off offset:3072
	s_waitcnt vmcnt(2)
	v_pk_mul_f32 v[2:3], v[34:35], v[2:3]
	s_waitcnt vmcnt(1)
	v_pk_add_f32 v[26:27], v[26:27], 1.0 op_sel_hi:[1,0]
	v_pk_mul_f32 v[4:5], v[36:37], v[4:5]
	v_pk_add_f32 v[28:29], v[28:29], 1.0 op_sel_hi:[1,0]
	s_waitcnt vmcnt(0)
	v_pk_fma_f32 v[2:3], v[2:3], v[26:27], v[30:31]
	v_pk_fma_f32 v[4:5], v[4:5], v[28:29], v[32:33]
	v_cvt_pk_bf16_f32 v2, v2, v3
	v_cvt_pk_bf16_f32 v3, v4, v5
	global_store_dwordx2 v[20:21], v[2:3], off offset:1536
